# v100 with P0 input loads as sc1 nt (agent scope, non-temporal) instead of nt
# speedup vs baseline: 1.0019x; 1.0019x over previous
; #define LAS __attribute__((address_space(3)))
; __device__ __forceinline__ unsigned pk_bf16(float lo, float hi) { typedef __bf16 b2 __attribute__((ext_vector_type(2))); f32x2 v = {lo, hi}; b2 b = __builtin_convertvector(v, b2); return __builtin_bit_cast(unsigned, b); }
; template <bool MAP> __device__ __forceinline__ void p0_transpose_item(const float* W, int K, int N, u16* WT, LAS float* scr, int item, int lane) {
;     const int nblk = N / 32, kb = item / nblk, nb = item % nblk, k0 = 64 * kb, n0 = 32 * nb;
;     float tv[32];
; #pragma unroll
;     for (int i = 0; i < 32; ++i) tv[i] = W[(size_t)(k0 + 2 * i + (lane >> 5)) * N + n0 + (lane & 31)];
; #pragma unroll
;     for (int i = 0; i < 32; ++i) scr[(2 * i + (lane >> 5)) * 33 + (lane & 31)] = tv[i];
;     asm volatile("s_waitcnt lgkmcnt(0)" ::: "memory");
;     const int c = lane & 7;
; #pragma unroll
;     for (int j = 0; j < 4; ++j) { const int n = (lane >> 3) + 8 * j; const LAS float* s = scr + (8 * c) * 33 + n;
;         u32x4 o; o.x = pk_bf16(s[0 * 33], s[1 * 33]); o.y = pk_bf16(s[2 * 33], s[3 * 33]); o.z = pk_bf16(s[4 * 33], s[5 * 33]); o.w = pk_bf16(s[6 * 33], s[7 * 33]);
; __device__ __forceinline__ void p0_prologue(const Ptrs& P, LAS unsigned char* lds, int vcu, int G) {
;     ...
;     for (int it = gw; it < NITEMS; it += NGW) {
;         int r = it;
;         if (r < I_IN) { p0_transpose_item<true>(P.w_in, 1024, NIN, (u16*)(P.ws + WS_WT), scr, r, lane); continue; } r -= I_IN;
;         if (r < I_A) { p0_transpose_item<false>(P.wa, 1024, 1024, (u16*)(P.ws + WS_WA), scr, r, lane); continue; } r -= I_A;
;         if (r < I_B) { p0_transpose_item<false>(P.wb, 512, 1024, (u16*)(P.ws + WS_WB), scr, r, lane); continue; } r -= I_B;
;         p0_transpose_item<false>(P.wo, 1024, 1024, (u16*)(P.ws + WS_WO), scr, r, lane);
.LBB0_24:
	s_cmpk_gt_i32 s28, 0x15ff
	s_mov_b64 s[8:9], -1
	s_cbranch_scc0 .LBB0_34
	s_cmpk_gt_u32 s28, 0x17ff
	s_cbranch_scc0 .LBB0_31
	s_cmpk_gt_u32 s28, 0x18ff
	s_cbranch_scc0 .LBB0_28
	s_add_i32 s8, s18, 0xfffce000
	s_and_b32 s8, s8, 0x3e0
	s_and_b32 s9, s21, 0xf0000
	s_or_b32 s9, s9, s8
	v_or_b32_e32 v0, s9, v26
	v_or_b32_e32 v14, s9, v29
	v_or_b32_e32 v15, s9, v30
	v_or_b32_e32 v16, s9, v31
	v_or_b32_e32 v17, s9, v32
	v_or_b32_e32 v18, s9, v33
	v_lshlrev_b32_e32 v0, 2, v0
	v_or_b32_e32 v12, s9, v27
	v_or_b32_e32 v13, s9, v28
	v_lshlrev_b32_e32 v14, 2, v14
	v_lshlrev_b32_e32 v15, 2, v15
	v_lshlrev_b32_e32 v16, 2, v16
	v_lshlrev_b32_e32 v17, 2, v17
	v_lshlrev_b32_e32 v18, 2, v18
	v_lshlrev_b32_e32 v12, 2, v12
	v_lshlrev_b32_e32 v13, 2, v13
	global_load_dword v19, v0, s[72:73] sc1 nt
	global_load_dword v20, v12, s[72:73] sc1 nt
	global_load_dword v21, v13, s[72:73] sc1 nt
	s_nop 0
	global_load_dword v14, v14, s[72:73] sc1 nt
	s_nop 0
	global_load_dword v15, v15, s[72:73] sc1 nt
	s_nop 0
	global_load_dword v16, v16, s[72:73] sc1 nt
	s_nop 0
	global_load_dword v17, v17, s[72:73] sc1 nt
	s_nop 0
	global_load_dword v18, v18, s[72:73] sc1 nt
	v_or_b32_e32 v0, s9, v34
	v_or_b32_e32 v22, s9, v37
	v_or_b32_e32 v23, s9, v38
	v_or_b32_e32 v71, s9, v39
	v_or_b32_e32 v72, s9, v40
	v_or_b32_e32 v73, s9, v41
	v_lshlrev_b32_e32 v0, 2, v0
	v_or_b32_e32 v12, s9, v35
	v_or_b32_e32 v13, s9, v36
	v_lshlrev_b32_e32 v22, 2, v22
	v_lshlrev_b32_e32 v23, 2, v23
	v_lshlrev_b32_e32 v71, 2, v71
	v_lshlrev_b32_e32 v72, 2, v72
	v_lshlrev_b32_e32 v73, 2, v73
	v_lshlrev_b32_e32 v12, 2, v12
	v_lshlrev_b32_e32 v13, 2, v13
	global_load_dword v74, v0, s[72:73] sc1 nt
	global_load_dword v75, v12, s[72:73] sc1 nt
	global_load_dword v76, v13, s[72:73] sc1 nt
	s_nop 0
	global_load_dword v22, v22, s[72:73] sc1 nt
	s_nop 0
	global_load_dword v23, v23, s[72:73] sc1 nt
	s_nop 0
	global_load_dword v71, v71, s[72:73] sc1 nt
	s_nop 0
	global_load_dword v72, v72, s[72:73] sc1 nt
	s_nop 0
	global_load_dword v73, v73, s[72:73] sc1 nt
	v_or_b32_e32 v0, s9, v42
	v_or_b32_e32 v77, s9, v45
	v_or_b32_e32 v78, s9, v46
	v_or_b32_e32 v79, s9, v47
	v_or_b32_e32 v80, s9, v48
	v_or_b32_e32 v81, s9, v49
	v_lshlrev_b32_e32 v0, 2, v0
	v_or_b32_e32 v12, s9, v43
	v_or_b32_e32 v13, s9, v44
	v_lshlrev_b32_e32 v77, 2, v77
	v_lshlrev_b32_e32 v78, 2, v78
	v_lshlrev_b32_e32 v79, 2, v79
	v_lshlrev_b32_e32 v80, 2, v80
	v_lshlrev_b32_e32 v81, 2, v81
	v_lshlrev_b32_e32 v12, 2, v12
	v_lshlrev_b32_e32 v13, 2, v13
	global_load_dword v82, v0, s[72:73] sc1 nt
	global_load_dword v83, v12, s[72:73] sc1 nt
	global_load_dword v84, v13, s[72:73] sc1 nt
	s_nop 0
	global_load_dword v77, v77, s[72:73] sc1 nt
	s_nop 0
	global_load_dword v78, v78, s[72:73] sc1 nt
	s_nop 0
	global_load_dword v79, v79, s[72:73] sc1 nt
	s_nop 0
	global_load_dword v80, v80, s[72:73] sc1 nt
	s_nop 0
	global_load_dword v81, v81, s[72:73] sc1 nt
	v_or_b32_e32 v0, s9, v50
	v_lshlrev_b32_e32 v85, 2, v0
	v_or_b32_e32 v0, s9, v51
	v_lshlrev_b32_e32 v86, 2, v0
	v_or_b32_e32 v0, s9, v52
	v_lshlrev_b32_e32 v87, 2, v0
	v_or_b32_e32 v0, s9, v53
	v_lshlrev_b32_e32 v88, 2, v0
	v_or_b32_e32 v0, s9, v54
	s_and_b32 s6, s20, 0x3e0
	v_lshlrev_b32_e32 v89, 2, v0
	v_or_b32_e32 v0, s9, v55
	v_lshlrev_b32_e32 v90, 2, v0
	v_or_b32_e32 v0, s9, v56
	s_add_i32 s6, s6, s21
	v_lshlrev_b32_e32 v91, 2, v0
	v_add_u32_e32 v0, s6, v26
	v_or_b32_e32 v0, 0xf800, v0
	v_lshl_add_u64 v[12:13], v[0:1], 2, s[72:73]
	global_load_dword v0, v85, s[72:73] sc1 nt
	s_nop 0
	global_load_dword v85, v86, s[72:73] sc1 nt
	s_nop 0
	global_load_dword v86, v87, s[72:73] sc1 nt
	s_nop 0
	global_load_dword v87, v88, s[72:73] sc1 nt
	s_nop 0
	global_load_dword v88, v89, s[72:73] sc1 nt
	s_nop 0
	global_load_dword v89, v90, s[72:73] sc1 nt
	s_nop 0
	global_load_dword v90, v91, s[72:73] sc1 nt
	s_nop 0
	global_load_dword v12, v[12:13], off sc1 nt
	s_and_b32 s6, s23, 0x3c0
	s_lshl_b32 s6, s6, 1
	s_waitcnt vmcnt(30)
	ds_write2_b32 v62, v19, v20 offset1:66
	s_waitcnt vmcnt(28)
	ds_write2_b32 v62, v21, v14 offset0:132 offset1:198
	s_waitcnt vmcnt(26)
	ds_write2_b32 v64, v15, v16 offset0:8 offset1:74
	s_waitcnt vmcnt(24)
	ds_write2_b32 v64, v17, v18 offset0:140 offset1:206
	s_waitcnt vmcnt(22)
	ds_write2_b32 v65, v74, v75 offset0:16 offset1:82
	s_waitcnt vmcnt(20)
	ds_write2_b32 v65, v76, v22 offset0:148 offset1:214
	s_waitcnt vmcnt(18)
	ds_write2_b32 v66, v23, v71 offset0:24 offset1:90
	s_waitcnt vmcnt(16)
	ds_write2_b32 v66, v72, v73 offset0:156 offset1:222
	s_waitcnt vmcnt(14)
	ds_write2_b32 v67, v82, v83 offset0:32 offset1:98
	s_waitcnt vmcnt(12)
	ds_write2_b32 v67, v84, v77 offset0:164 offset1:230
	s_waitcnt vmcnt(10)
	ds_write2_b32 v68, v78, v79 offset0:40 offset1:106
	s_waitcnt vmcnt(8)
	ds_write2_b32 v68, v80, v81 offset0:172 offset1:238
	s_waitcnt vmcnt(6)
	ds_write2_b32 v69, v0, v85 offset0:48 offset1:114
	s_waitcnt vmcnt(4)
	ds_write2_b32 v69, v86, v87 offset0:180 offset1:246
	s_waitcnt vmcnt(2)
	ds_write2_b32 v70, v88, v89 offset0:56 offset1:122
	s_waitcnt vmcnt(0)
	ds_write2_b32 v70, v90, v12 offset0:188 offset1:254
	s_waitcnt lgkmcnt(0)
	ds_read2_b32 v[16:17], v63 offset0:33 offset1:41
	ds_read2_b32 v[18:19], v63 offset1:8
	ds_read2_b32 v[20:21], v63 offset0:66 offset1:74
	ds_read2_b32 v[22:23], v63 offset0:99 offset1:107
	ds_read2_b32 v[72:73], v63 offset0:132 offset1:140
	ds_read2_b32 v[74:75], v63 offset0:165 offset1:173
	ds_read2_b32 v[76:77], v63 offset0:198 offset1:206
	ds_read2_b32 v[78:79], v63 offset0:231 offset1:239
	v_or_b32_e32 v0, s8, v58
	v_lshl_add_u64 v[80:81], v[6:7], 0, s[6:7]
	v_lshlrev_b32_e32 v0, 11, v0
	s_waitcnt lgkmcnt(6)
	v_cvt_pk_bf16_f32 v12, v18, v16
	s_waitcnt lgkmcnt(4)
; #define LAS __attribute__((address_space(3)))
; __device__ __forceinline__ unsigned pk_bf16(float lo, float hi) { typedef __bf16 b2 __attribute__((ext_vector_type(2))); f32x2 v = {lo, hi}; b2 b = __builtin_convertvector(v, b2); return __builtin_bit_cast(unsigned, b); }
; template <bool MAP> __device__ __forceinline__ void p0_transpose_item(const float* W, int K, int N, u16* WT, LAS float* scr, int item, int lane) {
;     const int nblk = N / 32, kb = item / nblk, nb = item % nblk, k0 = 64 * kb, n0 = 32 * nb;
;     float tv[32];
; #pragma unroll
;     for (int i = 0; i < 32; ++i) tv[i] = W[(size_t)(k0 + 2 * i + (lane >> 5)) * N + n0 + (lane & 31)];
; #pragma unroll
;     for (int i = 0; i < 32; ++i) scr[(2 * i + (lane >> 5)) * 33 + (lane & 31)] = tv[i];
;     ...
;         u32x4 o; o.x = pk_bf16(s[0 * 33], s[1 * 33]); o.y = pk_bf16(s[2 * 33], s[3 * 33]); o.z = pk_bf16(s[4 * 33], s[5 * 33]); o.w = pk_bf16(s[6 * 33], s[7 * 33]);
;         const int r = MAP ? wt_row_of_col(n0 + n) : (n0 + n);
;         *(u32x4*)(WT + (size_t)r * K + k0 + 8 * c) = o; }
	v_cvt_pk_bf16_f32 v13, v20, v22
	s_waitcnt lgkmcnt(2)
	v_cvt_pk_bf16_f32 v14, v72, v74
	s_waitcnt lgkmcnt(0)
	v_cvt_pk_bf16_f32 v15, v76, v78
	v_lshl_add_u64 v[82:83], v[80:81], 0, v[0:1]
	global_store_dwordx4 v[82:83], v[12:15], off sc1
	v_or_b32_e32 v0, s8, v59
	v_lshlrev_b32_e32 v0, 11, v0
	v_cvt_pk_bf16_f32 v12, v19, v17
	v_cvt_pk_bf16_f32 v13, v21, v23
	v_cvt_pk_bf16_f32 v14, v73, v75
	v_cvt_pk_bf16_f32 v15, v77, v79
	ds_read2_b32 v[18:19], v63 offset0:49 offset1:57
	ds_read2_b32 v[20:21], v63 offset0:16 offset1:24
	ds_read2_b32 v[22:23], v63 offset0:82 offset1:90
	ds_read2_b32 v[72:73], v63 offset0:115 offset1:123
	ds_read2_b32 v[74:75], v63 offset0:148 offset1:156
	ds_read2_b32 v[76:77], v63 offset0:181 offset1:189
	ds_read2_b32 v[78:79], v63 offset0:214 offset1:222
	ds_read2_b32 v[82:83], v63 offset0:247 offset1:255
	v_lshl_add_u64 v[16:17], v[80:81], 0, v[0:1]
	v_or_b32_e32 v0, s8, v60
	v_lshlrev_b32_e32 v0, 11, v0
	global_store_dwordx4 v[16:17], v[12:15], off sc1
	v_lshl_add_u64 v[16:17], v[80:81], 0, v[0:1]
	v_or_b32_e32 v0, s8, v61
	s_waitcnt lgkmcnt(6)
	v_cvt_pk_bf16_f32 v12, v20, v18
	s_waitcnt lgkmcnt(4)
	v_cvt_pk_bf16_f32 v13, v22, v72
	s_waitcnt lgkmcnt(2)
	v_cvt_pk_bf16_f32 v14, v74, v76
	s_waitcnt lgkmcnt(0)
	v_cvt_pk_bf16_f32 v15, v78, v82
	v_lshlrev_b32_e32 v0, 11, v0
	global_store_dwordx4 v[16:17], v[12:15], off sc1
	v_lshl_add_u64 v[16:17], v[80:81], 0, v[0:1]
	s_mov_b64 s[8:9], 0
	v_cvt_pk_bf16_f32 v12, v21, v19
	v_cvt_pk_bf16_f32 v13, v23, v73
	v_cvt_pk_bf16_f32 v14, v75, v77
	v_cvt_pk_bf16_f32 v15, v79, v83
	global_store_dwordx4 v[16:17], v[12:15], off sc1
	s_waitcnt lgkmcnt(0)
.LBB0_28:
	s_andn2_b64 vcc, exec, s[8:9]
	s_cbranch_vccnz .LBB0_30
	s_add_i32 s8, s18, 0xfffd0000
	s_add_i32 s9, s21, 0xc80000
	s_and_b32 s8, s8, 0x3e0
	s_and_b32 s9, s9, 0xf0000
	s_or_b32 s9, s8, s9
	v_or_b32_e32 v0, s9, v26
	v_or_b32_e32 v14, s9, v29
	v_or_b32_e32 v15, s9, v30
	v_or_b32_e32 v16, s9, v31
	v_or_b32_e32 v17, s9, v32
	v_or_b32_e32 v18, s9, v33
	v_lshlrev_b32_e32 v0, 2, v0
	v_or_b32_e32 v12, s9, v27
	v_or_b32_e32 v13, s9, v28
	v_lshlrev_b32_e32 v14, 2, v14
	v_lshlrev_b32_e32 v15, 2, v15
	v_lshlrev_b32_e32 v16, 2, v16
	v_lshlrev_b32_e32 v17, 2, v17
	v_lshlrev_b32_e32 v18, 2, v18
	v_lshlrev_b32_e32 v12, 2, v12
	v_lshlrev_b32_e32 v13, 2, v13
	global_load_dword v19, v0, s[70:71] sc1 nt
	global_load_dword v20, v12, s[70:71] sc1 nt
	global_load_dword v21, v13, s[70:71] sc1 nt
	s_nop 0
	global_load_dword v14, v14, s[70:71] sc1 nt
	s_nop 0
	global_load_dword v15, v15, s[70:71] sc1 nt
	s_nop 0
	global_load_dword v16, v16, s[70:71] sc1 nt
	s_nop 0
	global_load_dword v17, v17, s[70:71] sc1 nt
	s_nop 0
	global_load_dword v18, v18, s[70:71] sc1 nt
	v_or_b32_e32 v0, s9, v34
	v_or_b32_e32 v22, s9, v37
	v_or_b32_e32 v23, s9, v38
	v_or_b32_e32 v71, s9, v39
	v_or_b32_e32 v72, s9, v40
	v_or_b32_e32 v73, s9, v41
	v_lshlrev_b32_e32 v0, 2, v0
	v_or_b32_e32 v12, s9, v35
	v_or_b32_e32 v13, s9, v36
	v_lshlrev_b32_e32 v22, 2, v22
	v_lshlrev_b32_e32 v23, 2, v23
	v_lshlrev_b32_e32 v71, 2, v71
	v_lshlrev_b32_e32 v72, 2, v72
	v_lshlrev_b32_e32 v73, 2, v73
	v_lshlrev_b32_e32 v12, 2, v12
	v_lshlrev_b32_e32 v13, 2, v13
	global_load_dword v74, v0, s[70:71] sc1 nt
	global_load_dword v75, v12, s[70:71] sc1 nt
	global_load_dword v76, v13, s[70:71] sc1 nt
	s_nop 0
	global_load_dword v22, v22, s[70:71] sc1 nt
	s_nop 0
	global_load_dword v23, v23, s[70:71] sc1 nt
	s_nop 0
	global_load_dword v71, v71, s[70:71] sc1 nt
	s_nop 0
	global_load_dword v72, v72, s[70:71] sc1 nt
	s_nop 0
	global_load_dword v73, v73, s[70:71] sc1 nt
	v_or_b32_e32 v0, s9, v42
	v_or_b32_e32 v77, s9, v45
	v_or_b32_e32 v78, s9, v46
	v_or_b32_e32 v79, s9, v47
	v_or_b32_e32 v80, s9, v48
	v_or_b32_e32 v81, s9, v49
	v_lshlrev_b32_e32 v0, 2, v0
	v_or_b32_e32 v12, s9, v43
	v_or_b32_e32 v13, s9, v44
	v_lshlrev_b32_e32 v77, 2, v77
	v_lshlrev_b32_e32 v78, 2, v78
	v_lshlrev_b32_e32 v79, 2, v79
	v_lshlrev_b32_e32 v80, 2, v80
	v_lshlrev_b32_e32 v81, 2, v81
	v_lshlrev_b32_e32 v12, 2, v12
	v_lshlrev_b32_e32 v13, 2, v13
	global_load_dword v82, v0, s[70:71] sc1 nt
	global_load_dword v83, v12, s[70:71] sc1 nt
	global_load_dword v84, v13, s[70:71] sc1 nt
	s_nop 0
	global_load_dword v77, v77, s[70:71] sc1 nt
	s_nop 0
	global_load_dword v78, v78, s[70:71] sc1 nt
	s_nop 0
	global_load_dword v79, v79, s[70:71] sc1 nt
	s_nop 0
	global_load_dword v80, v80, s[70:71] sc1 nt
	s_nop 0
	global_load_dword v81, v81, s[70:71] sc1 nt
	v_or_b32_e32 v0, s9, v50
	v_lshlrev_b32_e32 v85, 2, v0
	v_or_b32_e32 v0, s9, v51
	v_lshlrev_b32_e32 v86, 2, v0
	v_or_b32_e32 v0, s9, v52
	v_lshlrev_b32_e32 v87, 2, v0
	v_or_b32_e32 v0, s9, v53
	v_lshlrev_b32_e32 v88, 2, v0
	v_or_b32_e32 v0, s9, v54
	s_and_b32 s6, s25, 0x3e0
	v_lshlrev_b32_e32 v89, 2, v0
	v_or_b32_e32 v0, s9, v55
	v_lshlrev_b32_e32 v90, 2, v0
	v_or_b32_e32 v0, s9, v56
	s_add_i32 s6, s6, s21
	v_lshlrev_b32_e32 v91, 2, v0
	v_add_u32_e32 v0, s6, v26
	v_add_u32_e32 v0, 0x80000, v0
	v_or_b32_e32 v0, 0xf800, v0
	v_lshl_add_u64 v[12:13], v[0:1], 2, s[70:71]
	global_load_dword v0, v85, s[70:71] sc1 nt
	s_nop 0
	global_load_dword v85, v86, s[70:71] sc1 nt
	s_nop 0
	global_load_dword v86, v87, s[70:71] sc1 nt
	s_nop 0
	global_load_dword v87, v88, s[70:71] sc1 nt
	s_nop 0
	global_load_dword v88, v89, s[70:71] sc1 nt
	s_nop 0
	global_load_dword v89, v90, s[70:71] sc1 nt
	s_nop 0
	global_load_dword v90, v91, s[70:71] sc1 nt
	s_nop 0
	global_load_dword v12, v[12:13], off sc1 nt
	s_add_i32 s6, s23, 0x200
	s_and_b32 s6, s6, 0x3c0
	s_lshl_b32 s6, s6, 1
	s_waitcnt vmcnt(30)
; #define LAS __attribute__((address_space(3)))
; __device__ __forceinline__ unsigned pk_bf16(float lo, float hi) { typedef __bf16 b2 __attribute__((ext_vector_type(2))); f32x2 v = {lo, hi}; b2 b = __builtin_convertvector(v, b2); return __builtin_bit_cast(unsigned, b); }
; template <bool MAP> __device__ __forceinline__ void p0_transpose_item(const float* W, int K, int N, u16* WT, LAS float* scr, int item, int lane) {
;     ...
;     for (int i = 0; i < 32; ++i) scr[(2 * i + (lane >> 5)) * 33 + (lane & 31)] = tv[i];
;     asm volatile("s_waitcnt lgkmcnt(0)" ::: "memory");
;     const int c = lane & 7;
; #pragma unroll
;     for (int j = 0; j < 4; ++j) { const int n = (lane >> 3) + 8 * j; const LAS float* s = scr + (8 * c) * 33 + n;
;         u32x4 o; o.x = pk_bf16(s[0 * 33], s[1 * 33]); o.y = pk_bf16(s[2 * 33], s[3 * 33]); o.z = pk_bf16(s[4 * 33], s[5 * 33]); o.w = pk_bf16(s[6 * 33], s[7 * 33]);
;         const int r = MAP ? wt_row_of_col(n0 + n) : (n0 + n);
;         *(u32x4*)(WT + (size_t)r * K + k0 + 8 * c) = o; }
	ds_write2_b32 v62, v19, v20 offset1:66
	s_waitcnt vmcnt(28)
	ds_write2_b32 v62, v21, v14 offset0:132 offset1:198
	s_waitcnt vmcnt(26)
	ds_write2_b32 v64, v15, v16 offset0:8 offset1:74
	s_waitcnt vmcnt(24)
	ds_write2_b32 v64, v17, v18 offset0:140 offset1:206
	s_waitcnt vmcnt(22)
	ds_write2_b32 v65, v74, v75 offset0:16 offset1:82
	s_waitcnt vmcnt(20)
	ds_write2_b32 v65, v76, v22 offset0:148 offset1:214
	s_waitcnt vmcnt(18)
	ds_write2_b32 v66, v23, v71 offset0:24 offset1:90
	s_waitcnt vmcnt(16)
	ds_write2_b32 v66, v72, v73 offset0:156 offset1:222
	s_waitcnt vmcnt(14)
	ds_write2_b32 v67, v82, v83 offset0:32 offset1:98
	s_waitcnt vmcnt(12)
	ds_write2_b32 v67, v84, v77 offset0:164 offset1:230
	s_waitcnt vmcnt(10)
	ds_write2_b32 v68, v78, v79 offset0:40 offset1:106
	s_waitcnt vmcnt(8)
	ds_write2_b32 v68, v80, v81 offset0:172 offset1:238
	s_waitcnt vmcnt(6)
	ds_write2_b32 v69, v0, v85 offset0:48 offset1:114
	s_waitcnt vmcnt(4)
	ds_write2_b32 v69, v86, v87 offset0:180 offset1:246
	s_waitcnt vmcnt(2)
	ds_write2_b32 v70, v88, v89 offset0:56 offset1:122
	s_waitcnt vmcnt(0)
	ds_write2_b32 v70, v90, v12 offset0:188 offset1:254
	s_waitcnt lgkmcnt(0)
	ds_read2_b32 v[16:17], v63 offset0:33 offset1:41
	ds_read2_b32 v[18:19], v63 offset1:8
	ds_read2_b32 v[20:21], v63 offset0:66 offset1:74
	ds_read2_b32 v[22:23], v63 offset0:99 offset1:107
	ds_read2_b32 v[72:73], v63 offset0:132 offset1:140
	ds_read2_b32 v[74:75], v63 offset0:165 offset1:173
	ds_read2_b32 v[76:77], v63 offset0:198 offset1:206
	ds_read2_b32 v[78:79], v63 offset0:231 offset1:239
	v_or_b32_e32 v0, s8, v58
	v_lshl_add_u64 v[80:81], v[8:9], 0, s[6:7]
	v_lshlrev_b32_e32 v0, 10, v0
	s_waitcnt lgkmcnt(6)
	v_cvt_pk_bf16_f32 v12, v18, v16
	s_waitcnt lgkmcnt(4)
	v_cvt_pk_bf16_f32 v13, v20, v22
	s_waitcnt lgkmcnt(2)
	v_cvt_pk_bf16_f32 v14, v72, v74
	s_waitcnt lgkmcnt(0)
	v_cvt_pk_bf16_f32 v15, v76, v78
	v_lshl_add_u64 v[82:83], v[80:81], 0, v[0:1]
	global_store_dwordx4 v[82:83], v[12:15], off sc1
	v_or_b32_e32 v0, s8, v59
	v_lshlrev_b32_e32 v0, 10, v0
	v_cvt_pk_bf16_f32 v12, v19, v17
	v_cvt_pk_bf16_f32 v13, v21, v23
	v_cvt_pk_bf16_f32 v14, v73, v75
	v_cvt_pk_bf16_f32 v15, v77, v79
	ds_read2_b32 v[18:19], v63 offset0:49 offset1:57
	ds_read2_b32 v[20:21], v63 offset0:16 offset1:24
	ds_read2_b32 v[22:23], v63 offset0:82 offset1:90
	ds_read2_b32 v[72:73], v63 offset0:115 offset1:123
	ds_read2_b32 v[74:75], v63 offset0:148 offset1:156
	ds_read2_b32 v[76:77], v63 offset0:181 offset1:189
	ds_read2_b32 v[78:79], v63 offset0:214 offset1:222
	ds_read2_b32 v[82:83], v63 offset0:247 offset1:255
	v_lshl_add_u64 v[16:17], v[80:81], 0, v[0:1]
	v_or_b32_e32 v0, s8, v60
	v_lshlrev_b32_e32 v0, 10, v0
	global_store_dwordx4 v[16:17], v[12:15], off sc1
	v_lshl_add_u64 v[16:17], v[80:81], 0, v[0:1]
	v_or_b32_e32 v0, s8, v61
	s_waitcnt lgkmcnt(6)
	v_cvt_pk_bf16_f32 v12, v20, v18
	s_waitcnt lgkmcnt(4)
	v_cvt_pk_bf16_f32 v13, v22, v72
	s_waitcnt lgkmcnt(2)
	v_cvt_pk_bf16_f32 v14, v74, v76
	s_waitcnt lgkmcnt(0)
	v_cvt_pk_bf16_f32 v15, v78, v82
	v_lshlrev_b32_e32 v0, 10, v0
	global_store_dwordx4 v[16:17], v[12:15], off sc1
	v_lshl_add_u64 v[16:17], v[80:81], 0, v[0:1]
	s_nop 0
	v_cvt_pk_bf16_f32 v12, v21, v19
	v_cvt_pk_bf16_f32 v13, v23, v73
	v_cvt_pk_bf16_f32 v14, v75, v77
	v_cvt_pk_bf16_f32 v15, v79, v83
	global_store_dwordx4 v[16:17], v[12:15], off sc1
	s_waitcnt lgkmcnt(0)

; #define LAS __attribute__((address_space(3)))
; template <bool MAP> __device__ __forceinline__ void p0_transpose_item(const float* W, int K, int N, u16* WT, LAS float* scr, int item, int lane) {
;     const int nblk = N / 32, kb = item / nblk, nb = item % nblk, k0 = 64 * kb, n0 = 32 * nb;
;     float tv[32];
; #pragma unroll
;     for (int i = 0; i < 32; ++i) tv[i] = W[(size_t)(k0 + 2 * i + (lane >> 5)) * N + n0 + (lane & 31)];
; #pragma unroll
;     for (int i = 0; i < 32; ++i) scr[(2 * i + (lane >> 5)) * 33 + (lane & 31)] = tv[i];
.LBB0_31:
	s_andn2_b64 vcc, exec, s[8:9]
	s_cbranch_vccnz .LBB0_33
	s_add_i32 s8, s18, 0xfffd4000
	s_add_i32 s9, s21, 0xc80000
	s_and_b32 s8, s8, 0x3e0
	s_and_b32 s9, s9, 0xf0000
	s_or_b32 s9, s8, s9
	v_or_b32_e32 v0, s9, v26
	v_or_b32_e32 v14, s9, v29
	v_or_b32_e32 v15, s9, v30
	v_or_b32_e32 v16, s9, v31
	v_or_b32_e32 v17, s9, v32
	v_or_b32_e32 v18, s9, v33
	v_lshlrev_b32_e32 v0, 2, v0
	v_or_b32_e32 v12, s9, v27
	v_or_b32_e32 v13, s9, v28
	v_lshlrev_b32_e32 v14, 2, v14
	v_lshlrev_b32_e32 v15, 2, v15
	v_lshlrev_b32_e32 v16, 2, v16
	v_lshlrev_b32_e32 v17, 2, v17
	v_lshlrev_b32_e32 v18, 2, v18
	v_lshlrev_b32_e32 v12, 2, v12
	v_lshlrev_b32_e32 v13, 2, v13
	global_load_dword v19, v0, s[68:69] sc1 nt
	global_load_dword v20, v12, s[68:69] sc1 nt
	global_load_dword v21, v13, s[68:69] sc1 nt
	s_nop 0
	global_load_dword v14, v14, s[68:69] sc1 nt
	s_nop 0
	global_load_dword v15, v15, s[68:69] sc1 nt
	s_nop 0
	global_load_dword v16, v16, s[68:69] sc1 nt
	s_nop 0
	global_load_dword v17, v17, s[68:69] sc1 nt
	s_nop 0
	global_load_dword v18, v18, s[68:69] sc1 nt
	v_or_b32_e32 v0, s9, v34
	v_or_b32_e32 v22, s9, v37
	v_or_b32_e32 v23, s9, v38
	v_or_b32_e32 v71, s9, v39
	v_or_b32_e32 v72, s9, v40
	v_or_b32_e32 v73, s9, v41
	v_lshlrev_b32_e32 v0, 2, v0
	v_or_b32_e32 v12, s9, v35
	v_or_b32_e32 v13, s9, v36
	v_lshlrev_b32_e32 v22, 2, v22
	v_lshlrev_b32_e32 v23, 2, v23
	v_lshlrev_b32_e32 v71, 2, v71
	v_lshlrev_b32_e32 v72, 2, v72
	v_lshlrev_b32_e32 v73, 2, v73
	v_lshlrev_b32_e32 v12, 2, v12
	v_lshlrev_b32_e32 v13, 2, v13
	global_load_dword v74, v0, s[68:69] sc1 nt
	global_load_dword v75, v12, s[68:69] sc1 nt
	global_load_dword v76, v13, s[68:69] sc1 nt
	s_nop 0
	global_load_dword v22, v22, s[68:69] sc1 nt
	s_nop 0
	global_load_dword v23, v23, s[68:69] sc1 nt
	s_nop 0
	global_load_dword v71, v71, s[68:69] sc1 nt
	s_nop 0
	global_load_dword v72, v72, s[68:69] sc1 nt
	s_nop 0
	global_load_dword v73, v73, s[68:69] sc1 nt
	v_or_b32_e32 v0, s9, v42
	v_or_b32_e32 v77, s9, v45
	v_or_b32_e32 v78, s9, v46
	v_or_b32_e32 v79, s9, v47
	v_or_b32_e32 v80, s9, v48
	v_or_b32_e32 v81, s9, v49
	v_lshlrev_b32_e32 v0, 2, v0
	v_or_b32_e32 v12, s9, v43
	v_or_b32_e32 v13, s9, v44
	v_lshlrev_b32_e32 v77, 2, v77
	v_lshlrev_b32_e32 v78, 2, v78
	v_lshlrev_b32_e32 v79, 2, v79
	v_lshlrev_b32_e32 v80, 2, v80
	v_lshlrev_b32_e32 v81, 2, v81
	v_lshlrev_b32_e32 v12, 2, v12
	v_lshlrev_b32_e32 v13, 2, v13
	global_load_dword v82, v0, s[68:69] sc1 nt
	global_load_dword v83, v12, s[68:69] sc1 nt
	global_load_dword v84, v13, s[68:69] sc1 nt
	s_nop 0
	global_load_dword v77, v77, s[68:69] sc1 nt
	s_nop 0
	global_load_dword v78, v78, s[68:69] sc1 nt
	s_nop 0
	global_load_dword v79, v79, s[68:69] sc1 nt
	s_nop 0
	global_load_dword v80, v80, s[68:69] sc1 nt
	s_nop 0
	global_load_dword v81, v81, s[68:69] sc1 nt
	v_or_b32_e32 v0, s9, v50
	v_lshlrev_b32_e32 v85, 2, v0
	v_or_b32_e32 v0, s9, v51
	v_lshlrev_b32_e32 v86, 2, v0
	v_or_b32_e32 v0, s9, v52
	v_lshlrev_b32_e32 v87, 2, v0
	v_or_b32_e32 v0, s9, v53
	v_lshlrev_b32_e32 v88, 2, v0
	v_or_b32_e32 v0, s9, v54
	s_and_b32 s6, s26, 0x3e0
	v_lshlrev_b32_e32 v89, 2, v0
	v_or_b32_e32 v0, s9, v55
	v_lshlrev_b32_e32 v90, 2, v0
	v_or_b32_e32 v0, s9, v56
	s_add_i32 s6, s6, s21
	v_lshlrev_b32_e32 v91, 2, v0
	v_add_u32_e32 v0, s6, v26
	v_add_u32_e32 v0, 0x180000, v0
	v_or_b32_e32 v0, 0xf800, v0
	v_lshl_add_u64 v[12:13], v[0:1], 2, s[68:69]
	global_load_dword v0, v85, s[68:69] sc1 nt
	s_nop 0
	global_load_dword v85, v86, s[68:69] sc1 nt
	s_nop 0
	global_load_dword v86, v87, s[68:69] sc1 nt
	s_nop 0
	global_load_dword v87, v88, s[68:69] sc1 nt
	s_nop 0
	global_load_dword v88, v89, s[68:69] sc1 nt
	s_nop 0
	global_load_dword v89, v90, s[68:69] sc1 nt
	s_nop 0
	global_load_dword v90, v91, s[68:69] sc1 nt
	s_nop 0
	global_load_dword v12, v[12:13], off sc1 nt
	s_add_i32 s6, s23, 0x600
	s_and_b32 s6, s6, 0x3c0
	s_lshl_b32 s6, s6, 1
	s_waitcnt vmcnt(30)
; #define LAS __attribute__((address_space(3)))
; __device__ __forceinline__ unsigned pk_bf16(float lo, float hi) { typedef __bf16 b2 __attribute__((ext_vector_type(2))); f32x2 v = {lo, hi}; b2 b = __builtin_convertvector(v, b2); return __builtin_bit_cast(unsigned, b); }
; template <bool MAP> __device__ __forceinline__ void p0_transpose_item(const float* W, int K, int N, u16* WT, LAS float* scr, int item, int lane) {
;     ...
;     for (int i = 0; i < 32; ++i) scr[(2 * i + (lane >> 5)) * 33 + (lane & 31)] = tv[i];
;     asm volatile("s_waitcnt lgkmcnt(0)" ::: "memory");
;     const int c = lane & 7;
; #pragma unroll
;     for (int j = 0; j < 4; ++j) { const int n = (lane >> 3) + 8 * j; const LAS float* s = scr + (8 * c) * 33 + n;
;         u32x4 o; o.x = pk_bf16(s[0 * 33], s[1 * 33]); o.y = pk_bf16(s[2 * 33], s[3 * 33]); o.z = pk_bf16(s[4 * 33], s[5 * 33]); o.w = pk_bf16(s[6 * 33], s[7 * 33]);
;         const int r = MAP ? wt_row_of_col(n0 + n) : (n0 + n);
;         *(u32x4*)(WT + (size_t)r * K + k0 + 8 * c) = o; }
	ds_write2_b32 v62, v19, v20 offset1:66
	s_waitcnt vmcnt(28)
	ds_write2_b32 v62, v21, v14 offset0:132 offset1:198
	s_waitcnt vmcnt(26)
	ds_write2_b32 v64, v15, v16 offset0:8 offset1:74
	s_waitcnt vmcnt(24)
	ds_write2_b32 v64, v17, v18 offset0:140 offset1:206
	s_waitcnt vmcnt(22)
	ds_write2_b32 v65, v74, v75 offset0:16 offset1:82
	s_waitcnt vmcnt(20)
	ds_write2_b32 v65, v76, v22 offset0:148 offset1:214
	s_waitcnt vmcnt(18)
	ds_write2_b32 v66, v23, v71 offset0:24 offset1:90
	s_waitcnt vmcnt(16)
	ds_write2_b32 v66, v72, v73 offset0:156 offset1:222
	s_waitcnt vmcnt(14)
	ds_write2_b32 v67, v82, v83 offset0:32 offset1:98
	s_waitcnt vmcnt(12)
	ds_write2_b32 v67, v84, v77 offset0:164 offset1:230
	s_waitcnt vmcnt(10)
	ds_write2_b32 v68, v78, v79 offset0:40 offset1:106
	s_waitcnt vmcnt(8)
	ds_write2_b32 v68, v80, v81 offset0:172 offset1:238
	s_waitcnt vmcnt(6)
	ds_write2_b32 v69, v0, v85 offset0:48 offset1:114
	s_waitcnt vmcnt(4)
	ds_write2_b32 v69, v86, v87 offset0:180 offset1:246
	s_waitcnt vmcnt(2)
	ds_write2_b32 v70, v88, v89 offset0:56 offset1:122
	s_waitcnt vmcnt(0)
	ds_write2_b32 v70, v90, v12 offset0:188 offset1:254
	s_waitcnt lgkmcnt(0)
	ds_read2_b32 v[16:17], v63 offset0:33 offset1:41
	ds_read2_b32 v[18:19], v63 offset1:8
	ds_read2_b32 v[20:21], v63 offset0:66 offset1:74
	ds_read2_b32 v[22:23], v63 offset0:99 offset1:107
	ds_read2_b32 v[72:73], v63 offset0:132 offset1:140
	ds_read2_b32 v[74:75], v63 offset0:165 offset1:173
	ds_read2_b32 v[76:77], v63 offset0:198 offset1:206
	ds_read2_b32 v[78:79], v63 offset0:231 offset1:239
	v_or_b32_e32 v0, s8, v58
	v_lshl_add_u64 v[80:81], v[10:11], 0, s[6:7]
	v_lshlrev_b32_e32 v0, 11, v0
	s_waitcnt lgkmcnt(6)
	v_cvt_pk_bf16_f32 v12, v18, v16
	s_waitcnt lgkmcnt(4)
	v_cvt_pk_bf16_f32 v13, v20, v22
	s_waitcnt lgkmcnt(2)
	v_cvt_pk_bf16_f32 v14, v72, v74
	s_waitcnt lgkmcnt(0)
	v_cvt_pk_bf16_f32 v15, v76, v78
	v_lshl_add_u64 v[82:83], v[80:81], 0, v[0:1]
	global_store_dwordx4 v[82:83], v[12:15], off sc1
	v_or_b32_e32 v0, s8, v59
	v_lshlrev_b32_e32 v0, 11, v0
	v_cvt_pk_bf16_f32 v12, v19, v17
	v_cvt_pk_bf16_f32 v13, v21, v23
	v_cvt_pk_bf16_f32 v14, v73, v75
	v_cvt_pk_bf16_f32 v15, v77, v79
	ds_read2_b32 v[18:19], v63 offset0:49 offset1:57
	ds_read2_b32 v[20:21], v63 offset0:16 offset1:24
	ds_read2_b32 v[22:23], v63 offset0:82 offset1:90
	ds_read2_b32 v[72:73], v63 offset0:115 offset1:123
	ds_read2_b32 v[74:75], v63 offset0:148 offset1:156
	ds_read2_b32 v[76:77], v63 offset0:181 offset1:189
	ds_read2_b32 v[78:79], v63 offset0:214 offset1:222
	ds_read2_b32 v[82:83], v63 offset0:247 offset1:255
	v_lshl_add_u64 v[16:17], v[80:81], 0, v[0:1]
	v_or_b32_e32 v0, s8, v60
	v_lshlrev_b32_e32 v0, 11, v0
	global_store_dwordx4 v[16:17], v[12:15], off sc1
	v_lshl_add_u64 v[16:17], v[80:81], 0, v[0:1]
	v_or_b32_e32 v0, s8, v61
	s_waitcnt lgkmcnt(6)
	v_cvt_pk_bf16_f32 v12, v20, v18
	s_waitcnt lgkmcnt(4)
	v_cvt_pk_bf16_f32 v13, v22, v72
	s_waitcnt lgkmcnt(2)
	v_cvt_pk_bf16_f32 v14, v74, v76
	s_waitcnt lgkmcnt(0)
	v_cvt_pk_bf16_f32 v15, v78, v82
	v_lshlrev_b32_e32 v0, 11, v0
	global_store_dwordx4 v[16:17], v[12:15], off sc1
	v_lshl_add_u64 v[16:17], v[80:81], 0, v[0:1]
	s_nop 0
	v_cvt_pk_bf16_f32 v12, v21, v19
	v_cvt_pk_bf16_f32 v13, v23, v73
	v_cvt_pk_bf16_f32 v14, v75, v77
	v_cvt_pk_bf16_f32 v15, v79, v83
	global_store_dwordx4 v[16:17], v[12:15], off sc1
	s_waitcnt lgkmcnt(0)

; #define LAS __attribute__((address_space(3)))
; __device__ __forceinline__ unsigned pk_bf16(float lo, float hi) { typedef __bf16 b2 __attribute__((ext_vector_type(2))); f32x2 v = {lo, hi}; b2 b = __builtin_convertvector(v, b2); return __builtin_bit_cast(unsigned, b); }
; template <bool MAP> __device__ __forceinline__ void p0_transpose_item(const float* W, int K, int N, u16* WT, LAS float* scr, int item, int lane) {
;     const int nblk = N / 32, kb = item / nblk, nb = item % nblk, k0 = 64 * kb, n0 = 32 * nb;
;     float tv[32];
; #pragma unroll
;     for (int i = 0; i < 32; ++i) tv[i] = W[(size_t)(k0 + 2 * i + (lane >> 5)) * N + n0 + (lane & 31)];
; #pragma unroll
;     for (int i = 0; i < 32; ++i) scr[(2 * i + (lane >> 5)) * 33 + (lane & 31)] = tv[i];
;     asm volatile("s_waitcnt lgkmcnt(0)" ::: "memory");
;     const int c = lane & 7;
; #pragma unroll
;     for (int j = 0; j < 4; ++j) { const int n = (lane >> 3) + 8 * j; const LAS float* s = scr + (8 * c) * 33 + n;
;         u32x4 o; o.x = pk_bf16(s[0 * 33], s[1 * 33]); o.y = pk_bf16(s[2 * 33], s[3 * 33]); o.z = pk_bf16(s[4 * 33], s[5 * 33]); o.w = pk_bf16(s[6 * 33], s[7 * 33]);
;         const int r = MAP ? wt_row_of_col(n0 + n) : (n0 + n);
; __device__ __forceinline__ void p0_prologue(const Ptrs& P, LAS unsigned char* lds, int vcu, int G) {
;     ...
;     for (int it = gw; it < NITEMS; it += NGW) {
;         int r = it;
;         if (r < I_IN) { p0_transpose_item<true>(P.w_in, 1024, NIN, (u16*)(P.ws + WS_WT), scr, r, lane); continue; } r -= I_IN;
.LBB0_34:
	s_andn2_b64 vcc, exec, s[8:9]
	s_cbranch_vccnz .LBB0_23
	s_mul_hi_i32 s6, s28, 0x2e8ba2e9
	s_lshr_b32 s8, s6, 31
	s_ashr_i32 s6, s6, 6
	s_add_i32 s6, s6, s8
	s_mul_i32 s8, s6, 0xffffd400
	s_lshl_b32 s10, s6, 6
	s_add_i32 s8, s18, s8
	v_or_b32_e32 v0, s10, v57
	s_ashr_i32 s9, s8, 31
	v_lshl_add_u64 v[12:13], s[8:9], 2, v[2:3]
	v_or_b32_e32 v71, 10, v0
	v_mad_i64_i32 v[72:73], s[12:13], v71, s1, v[12:13]
	v_or_b32_e32 v71, 12, v0
	v_or_b32_e32 v16, 2, v0
	v_or_b32_e32 v18, 4, v0
	v_or_b32_e32 v20, 6, v0
	v_or_b32_e32 v22, 8, v0
	v_mad_i64_i32 v[74:75], s[12:13], v71, s1, v[12:13]
	v_or_b32_e32 v71, 14, v0
	v_mad_i64_i32 v[14:15], s[12:13], v0, s1, v[12:13]
	v_mad_i64_i32 v[16:17], s[12:13], v16, s1, v[12:13]
	v_mad_i64_i32 v[18:19], s[12:13], v18, s1, v[12:13]
	v_mad_i64_i32 v[20:21], s[12:13], v20, s1, v[12:13]
	v_mad_i64_i32 v[22:23], s[12:13], v22, s1, v[12:13]
	v_mad_i64_i32 v[76:77], s[12:13], v71, s1, v[12:13]
	global_load_dword v71, v[14:15], off sc1 nt
	global_load_dword v78, v[16:17], off sc1 nt
	global_load_dword v79, v[18:19], off sc1 nt
	global_load_dword v80, v[20:21], off sc1 nt
	global_load_dword v81, v[22:23], off sc1 nt
	global_load_dword v82, v[72:73], off sc1 nt
	global_load_dword v83, v[74:75], off sc1 nt
	global_load_dword v84, v[76:77], off sc1 nt
	v_or_b32_e32 v14, 16, v0
	v_or_b32_e32 v16, 18, v0
	v_or_b32_e32 v18, 20, v0
	v_or_b32_e32 v20, 22, v0
	v_or_b32_e32 v22, 24, v0
	v_or_b32_e32 v72, 26, v0
	v_or_b32_e32 v74, 28, v0
	v_or_b32_e32 v76, 30, v0
	v_mad_i64_i32 v[14:15], s[12:13], v14, s1, v[12:13]
	v_mad_i64_i32 v[16:17], s[12:13], v16, s1, v[12:13]
	v_mad_i64_i32 v[18:19], s[12:13], v18, s1, v[12:13]
	v_mad_i64_i32 v[20:21], s[12:13], v20, s1, v[12:13]
	v_mad_i64_i32 v[22:23], s[12:13], v22, s1, v[12:13]
	v_mad_i64_i32 v[72:73], s[12:13], v72, s1, v[12:13]
	v_mad_i64_i32 v[74:75], s[12:13], v74, s1, v[12:13]
	v_mad_i64_i32 v[76:77], s[12:13], v76, s1, v[12:13]
	global_load_dword v85, v[14:15], off sc1 nt
	global_load_dword v86, v[16:17], off sc1 nt
	global_load_dword v87, v[18:19], off sc1 nt
	global_load_dword v88, v[20:21], off sc1 nt
	global_load_dword v89, v[22:23], off sc1 nt
	global_load_dword v90, v[72:73], off sc1 nt
	global_load_dword v91, v[74:75], off sc1 nt
	global_load_dword v92, v[76:77], off sc1 nt
	v_or_b32_e32 v14, 32, v0
	v_or_b32_e32 v16, 34, v0
	v_or_b32_e32 v18, 36, v0
	v_or_b32_e32 v20, 38, v0
	v_or_b32_e32 v22, 40, v0
	v_or_b32_e32 v72, 42, v0
	v_or_b32_e32 v74, 44, v0
	v_or_b32_e32 v76, 46, v0
	v_mad_i64_i32 v[14:15], s[12:13], v14, s1, v[12:13]
	v_mad_i64_i32 v[16:17], s[12:13], v16, s1, v[12:13]
	v_mad_i64_i32 v[18:19], s[12:13], v18, s1, v[12:13]
	v_mad_i64_i32 v[20:21], s[12:13], v20, s1, v[12:13]
	v_mad_i64_i32 v[22:23], s[12:13], v22, s1, v[12:13]
	v_mad_i64_i32 v[72:73], s[12:13], v72, s1, v[12:13]
	v_mad_i64_i32 v[74:75], s[12:13], v74, s1, v[12:13]
	v_mad_i64_i32 v[76:77], s[12:13], v76, s1, v[12:13]
	global_load_dword v93, v[14:15], off sc1 nt
	global_load_dword v94, v[16:17], off sc1 nt
	global_load_dword v95, v[18:19], off sc1 nt
	global_load_dword v96, v[20:21], off sc1 nt
	global_load_dword v97, v[22:23], off sc1 nt
	global_load_dword v98, v[72:73], off sc1 nt
	global_load_dword v99, v[74:75], off sc1 nt
	s_nop 0
	global_load_dword v76, v[76:77], off sc1 nt
	v_or_b32_e32 v14, 48, v0
	v_or_b32_e32 v16, 50, v0
	v_or_b32_e32 v18, 52, v0
	v_or_b32_e32 v20, 54, v0
	v_or_b32_e32 v22, 56, v0
	v_or_b32_e32 v72, 58, v0
	v_or_b32_e32 v74, 60, v0
	v_or_b32_e32 v0, 62, v0
	v_mad_i64_i32 v[14:15], s[12:13], v14, s1, v[12:13]
	v_mad_i64_i32 v[16:17], s[12:13], v16, s1, v[12:13]
	v_mad_i64_i32 v[18:19], s[12:13], v18, s1, v[12:13]
	v_mad_i64_i32 v[20:21], s[12:13], v20, s1, v[12:13]
	v_mad_i64_i32 v[22:23], s[12:13], v22, s1, v[12:13]
	v_mad_i64_i32 v[72:73], s[12:13], v72, s1, v[12:13]
	v_mad_i64_i32 v[74:75], s[12:13], v74, s1, v[12:13]
	v_mad_i64_i32 v[12:13], s[12:13], v0, s1, v[12:13]
	global_load_dword v0, v[14:15], off sc1 nt
	s_nop 0
	global_load_dword v14, v[16:17], off sc1 nt
	global_load_dword v15, v[18:19], off sc1 nt
	s_nop 0
	global_load_dword v16, v[20:21], off sc1 nt
	global_load_dword v17, v[22:23], off sc1 nt
	global_load_dword v18, v[72:73], off sc1 nt
	global_load_dword v19, v[74:75], off sc1 nt
	s_nop 0
	global_load_dword v12, v[12:13], off sc1 nt
	s_waitcnt vmcnt(30)
	ds_write2_b32 v62, v71, v78 offset1:66
	s_waitcnt vmcnt(28)
	ds_write2_b32 v62, v79, v80 offset0:132 offset1:198
	s_waitcnt vmcnt(26)
	ds_write2_b32 v64, v81, v82 offset0:8 offset1:74
	s_waitcnt vmcnt(24)
	ds_write2_b32 v64, v83, v84 offset0:140 offset1:206
	s_waitcnt vmcnt(22)
	ds_write2_b32 v65, v85, v86 offset0:16 offset1:82
	s_waitcnt vmcnt(20)
	ds_write2_b32 v65, v87, v88 offset0:148 offset1:214
	s_waitcnt vmcnt(18)
	ds_write2_b32 v66, v89, v90 offset0:24 offset1:90
	s_waitcnt vmcnt(16)
	ds_write2_b32 v66, v91, v92 offset0:156 offset1:222
	s_waitcnt vmcnt(14)
	ds_write2_b32 v67, v93, v94 offset0:32 offset1:98
	s_waitcnt vmcnt(12)
	ds_write2_b32 v67, v95, v96 offset0:164 offset1:230
	s_waitcnt vmcnt(10)
	ds_write2_b32 v68, v97, v98 offset0:40 offset1:106
	s_waitcnt vmcnt(8)
	ds_write2_b32 v68, v99, v76 offset0:172 offset1:238
	s_waitcnt vmcnt(6)
	ds_write2_b32 v69, v0, v14 offset0:48 offset1:114
	s_waitcnt vmcnt(4)
	ds_write2_b32 v69, v15, v16 offset0:180 offset1:246
	s_waitcnt vmcnt(2)
	ds_write2_b32 v70, v17, v18 offset0:56 offset1:122
	s_waitcnt vmcnt(0)
	ds_write2_b32 v70, v19, v12 offset0:188 offset1:254
	s_waitcnt lgkmcnt(0)
	ds_read2_b32 v[14:15], v63 offset1:33
	ds_read2_b32 v[16:17], v63 offset0:66 offset1:99
	ds_read2_b32 v[18:19], v63 offset0:132 offset1:165
	ds_read2_b32 v[20:21], v63 offset0:198 offset1:231
	s_mulk_i32 s6, 0x160
	s_sub_i32 s6, s28, s6
	s_lshl_b32 s6, s6, 5
	v_add_u32_e32 v0, s8, v58
	v_or_b32_e32 v22, s6, v58
	v_cmp_lt_i32_e32 vcc, s27, v0
	s_and_saveexec_b64 s[12:13], vcc
	s_cbranch_execz .LBB0_40
	s_cmpk_lt_u32 s8, 0x2400
	s_mov_b64 s[14:15], -1
	s_cbranch_scc0 .LBB0_38
	v_and_b32_e32 v13, 39, v0
	v_lshlrev_b32_e32 v23, 1, v13
	v_add_u32_e32 v12, 0xfffff000, v0
	v_subrev_u32_e32 v71, 63, v23
	v_cmp_gt_u32_e32 vcc, 32, v13
	s_cmpk_lt_u32 s8, 0x1c00
	v_and_b32_e32 v22, 0xffffffc0, v12
	v_cndmask_b32_e32 v13, v71, v23, vcc
	v_add_u32_e32 v13, v13, v22
	s_cselect_b64 vcc, -1, 0
	v_cndmask_b32_e32 v12, v12, v13, vcc
	v_add_u32_e32 v22, 0x1800, v12
	s_mov_b64 s[14:15], 0

; __device__ __forceinline__ void p0_prologue(const Ptrs& P, LAS unsigned char* lds, int vcu, int G) {
;     ...
;     for (int m = gw; m < TT; m += 2 * NGW) {
;         const int m2 = (m + NGW < TT) ? m + NGW : m;
;         const f32x4* xr = (const f32x4*)(P.x + (size_t)m * DM) + lane; const f32x4* xr2 = (const f32x4*)(P.x + (size_t)m2 * DM) + lane; f32x4 v[4], v2[4]; float s = 0.f, s2 = 0.f;
; #pragma unroll
;         for (int j = 0; j < 4; ++j) { v[j] = xr[64 * j]; v2[j] = xr2[64 * j]; }
; #pragma unroll
;         for (int j = 0; j < 4; ++j) { s += (v[j].x * v[j].x + v[j].y * v[j].y) + (v[j].z * v[j].z + v[j].w * v[j].w); s2 += (v2[j].x * v2[j].x + v2[j].y * v2[j].y) + (v2[j].z * v2[j].z + v2[j].w * v2[j].w); }
;         const float rstd = rsqrtf(wave_sum(s) * (1.0f / DM) + NORM_EPS), rstd2 = rsqrtf(wave_sum(s2) * (1.0f / DM) + NORM_EPS);
.LBB0_57:
	s_add_i32 s8, s0, s17
	s_cmpk_lt_i32 s8, 0x4000
	s_cselect_b32 s10, s8, s0
	s_ashr_i32 s1, s0, 31
	s_lshl_b64 s[12:13], s[0:1], 12
	s_ashr_i32 s11, s10, 31
	v_lshl_add_u64 v[22:23], v[2:3], 0, s[12:13]
	s_lshl_b64 s[12:13], s[10:11], 12
	global_load_dwordx4 v[18:21], v[22:23], off sc1 nt
	global_load_dwordx4 v[26:29], v[22:23], off offset:1024 sc1 nt
	global_load_dwordx4 v[30:33], v[22:23], off offset:3072 sc1 nt
	global_load_dwordx4 v[34:37], v[22:23], off offset:2048 sc1 nt
	v_lshl_add_u64 v[22:23], v[2:3], 0, s[12:13]
	global_load_dwordx4 v[38:41], v[22:23], off sc1 nt
	global_load_dwordx4 v[42:45], v[22:23], off offset:1024 sc1 nt
	global_load_dwordx4 v[46:49], v[22:23], off offset:3072 sc1 nt
	global_load_dwordx4 v[50:53], v[22:23], off offset:2048 sc1 nt
	s_lshl_b64 s[0:1], s[0:1], 11
	v_lshl_add_u64 v[54:55], v[0:1], 0, s[0:1]
	s_lshl_b64 s[0:1], s[10:11], 11
	v_lshl_add_u64 v[56:57], v[0:1], 0, s[0:1]
	s_waitcnt vmcnt(7)
	v_pk_mul_f32 v[22:23], v[20:21], v[20:21]
	v_pk_mul_f32 v[58:59], v[18:19], v[18:19]
	s_waitcnt vmcnt(6)
	v_pk_mul_f32 v[60:61], v[28:29], v[28:29]
	v_pk_mul_f32 v[62:63], v[26:27], v[26:27]
	s_waitcnt vmcnt(4)
	v_mul_f32_e32 v64, v35, v35
	v_mul_f32_e32 v66, v37, v37
	v_pk_mov_b32 v[68:69], v[58:59], v[22:23] op_sel:[1,0]
	v_mov_b32_e32 v59, v23
	s_waitcnt vmcnt(3)
	v_pk_mul_f32 v[22:23], v[40:41], v[40:41]
	v_pk_mul_f32 v[70:71], v[38:39], v[38:39]
	v_pk_mov_b32 v[72:73], v[62:63], v[60:61] op_sel:[1,0]
	v_mov_b32_e32 v63, v61
	s_waitcnt vmcnt(2)
	v_pk_mul_f32 v[60:61], v[44:45], v[44:45]
	v_pk_mul_f32 v[74:75], v[42:43], v[42:43]
	v_mul_f32_e32 v77, v32, v32
	v_mul_f32_e32 v79, v33, v33
	v_pk_fma_f32 v[64:65], v[34:35], v[34:35], v[64:65] op_sel_hi:[1,1,0]
	v_pk_fma_f32 v[66:67], v[36:37], v[36:37], v[66:67] op_sel_hi:[1,1,0]
	v_pk_add_f32 v[58:59], v[68:69], v[58:59]
	v_pk_mov_b32 v[68:69], v[70:71], v[22:23] op_sel:[1,0]
	v_mov_b32_e32 v71, v23
	v_pk_add_f32 v[22:23], v[72:73], v[62:63]
	v_pk_mov_b32 v[62:63], v[74:75], v[60:61] op_sel:[1,0]
	v_mov_b32_e32 v75, v61
	s_waitcnt vmcnt(0)
	v_mul_f32_e32 v76, v51, v51
	v_mul_f32_e32 v78, v53, v53
	v_mov_b32_e32 v65, v77
	v_mov_b32_e32 v67, v79
	v_pk_add_f32 v[68:69], v[68:69], v[70:71]
	v_pk_add_f32 v[62:63], v[62:63], v[74:75]
	v_mul_f32_e32 v13, v30, v30
	v_mul_f32_e32 v25, v31, v31
	v_mul_f32_e32 v80, v46, v46
	v_mul_f32_e32 v81, v47, v47
	v_mul_f32_e32 v82, v48, v48
	v_mul_f32_e32 v83, v49, v49
	v_pk_fma_f32 v[60:61], v[50:51], v[50:51], v[76:77] op_sel_hi:[1,1,0]
	v_pk_fma_f32 v[72:73], v[52:53], v[52:53], v[78:79] op_sel_hi:[1,1,0]
	v_pk_add_f32 v[58:59], v[58:59], v[58:59] op_sel:[0,1] op_sel_hi:[1,0]
	v_pk_add_f32 v[22:23], v[22:23], v[22:23] op_sel:[0,1] op_sel_hi:[1,0]
	v_pk_add_f32 v[64:65], v[64:65], v[66:67]
	v_pk_add_f32 v[66:67], v[68:69], v[68:69] op_sel:[0,1] op_sel_hi:[1,0]
	v_pk_add_f32 v[62:63], v[62:63], v[62:63] op_sel:[0,1] op_sel_hi:[1,0]
	v_mov_b32_e32 v61, v82
	v_mov_b32_e32 v73, v83
	v_mov_b32_e32 v59, v13
	v_mov_b32_e32 v23, v25
	v_mov_b32_e32 v67, v80
	v_mov_b32_e32 v63, v81
	v_pk_add_f32 v[60:61], v[60:61], v[72:73]
	v_pk_add_f32 v[22:23], v[58:59], v[22:23]
	v_pk_add_f32 v[58:59], v[66:67], v[62:63]
	v_pk_add_f32 v[22:23], v[22:23], v[64:65]
	v_pk_add_f32 v[58:59], v[58:59], v[60:61]
	v_mov_b32_e32 v61, v22
	v_mov_b32_e32 v60, v58
	v_mov_b32_e32 v22, v59
	v_pk_add_f32 v[22:23], v[60:61], v[22:23]
	ds_bpermute_b32 v59, v7, v23
	ds_bpermute_b32 v58, v7, v22
	s_waitcnt lgkmcnt(0)
	v_pk_add_f32 v[22:23], v[22:23], v[58:59]
	ds_bpermute_b32 v59, v8, v23
	ds_bpermute_b32 v58, v8, v22
	s_waitcnt lgkmcnt(0)
	v_pk_add_f32 v[22:23], v[22:23], v[58:59]
	ds_bpermute_b32 v59, v9, v23
	ds_bpermute_b32 v58, v9, v22
	s_waitcnt lgkmcnt(0)
; __device__ __forceinline__ unsigned pk_bf16(float lo, float hi) { typedef __bf16 b2 __attribute__((ext_vector_type(2))); f32x2 v = {lo, hi}; b2 b = __builtin_convertvector(v, b2); return __builtin_bit_cast(unsigned, b); }
; __device__ __forceinline__ void p0_prologue(const Ptrs& P, LAS unsigned char* lds, int vcu, int G) {
;     ...
;         const float rstd = rsqrtf(wave_sum(s) * (1.0f / DM) + NORM_EPS), rstd2 = rsqrtf(wave_sum(s2) * (1.0f / DM) + NORM_EPS);
;         u32x2* o8 = (u32x2*)(H + (size_t)m * DM) + lane; u32x2* o82 = (u32x2*)(H + (size_t)m2 * DM) + lane;
; #pragma unroll
;         for (int j = 0; j < 4; ++j) { const f32x4 w4 = ((const f32x4*)P.norm_w)[lane + 64 * j];
;             o8[64 * j] = (u32x2){pk_bf16(v[j].x * rstd * w4.x, v[j].y * rstd * w4.y), pk_bf16(v[j].z * rstd * w4.z, v[j].w * rstd * w4.w)};
;             o82[64 * j] = (u32x2){pk_bf16(v2[j].x * rstd2 * w4.x, v2[j].y * rstd2 * w4.y), pk_bf16(v2[j].z * rstd2 * w4.z, v2[j].w * rstd2 * w4.w)}; }
	v_pk_add_f32 v[22:23], v[22:23], v[58:59]
	ds_bpermute_b32 v59, v10, v23
	ds_bpermute_b32 v58, v10, v22
	s_waitcnt lgkmcnt(0)
	v_pk_add_f32 v[22:23], v[22:23], v[58:59]
	ds_bpermute_b32 v59, v11, v23
	ds_bpermute_b32 v58, v11, v22
	s_waitcnt lgkmcnt(0)
	v_pk_add_f32 v[22:23], v[22:23], v[58:59]
	ds_bpermute_b32 v59, v12, v23
	ds_bpermute_b32 v58, v12, v22
	s_waitcnt lgkmcnt(0)
	v_pk_add_f32 v[22:23], v[22:23], v[58:59]
	s_nop 0
	v_pk_fma_f32 v[22:23], v[22:23], s[6:7], v[6:7] op_sel_hi:[1,0,0]
	s_nop 0
	v_mul_f32_e32 v13, 0x4b800000, v23
	v_cmp_gt_f32_e64 s[0:1], s7, v23
	v_mul_f32_e32 v25, 0x4b800000, v22
	v_cmp_gt_f32_e32 vcc, s7, v22
	v_cndmask_b32_e64 v13, v23, v13, s[0:1]
	v_rsq_f32_e32 v13, v13
	v_cndmask_b32_e32 v22, v22, v25, vcc
	v_rsq_f32_e32 v23, v22
	v_mul_f32_e32 v22, 0x45800000, v13
	v_cndmask_b32_e64 v22, v13, v22, s[0:1]
	v_mul_f32_e32 v25, 0x45800000, v23
	v_cndmask_b32_e32 v58, v23, v25, vcc
	v_pk_mul_f32 v[18:19], v[18:19], v[22:23] op_sel_hi:[1,0]
	v_pk_mul_f32 v[20:21], v[20:21], v[22:23] op_sel_hi:[1,0]
	v_pk_mul_f32 v[38:39], v[38:39], v[58:59] op_sel_hi:[1,0]
	v_pk_mul_f32 v[40:41], v[40:41], v[58:59] op_sel_hi:[1,0]
	v_pk_mul_f32 v[18:19], v[100:101], v[18:19]
	v_pk_mul_f32 v[20:21], v[102:103], v[20:21]
	v_pk_mul_f32 v[14:15], v[100:101], v[38:39]
	v_pk_mul_f32 v[16:17], v[102:103], v[40:41]
	v_cvt_pk_bf16_f32 v18, v18, v19
	v_cvt_pk_bf16_f32 v19, v20, v21
	v_cvt_pk_bf16_f32 v14, v14, v15
	v_cvt_pk_bf16_f32 v15, v16, v17
	global_store_dwordx2 v[54:55], v[18:19], off sc1
	global_store_dwordx2 v[56:57], v[14:15], off sc1
	v_pk_mul_f32 v[18:19], v[26:27], v[22:23] op_sel_hi:[1,0]
	v_pk_mul_f32 v[20:21], v[28:29], v[22:23] op_sel_hi:[1,0]
	v_pk_mul_f32 v[26:27], v[42:43], v[58:59] op_sel_hi:[1,0]
	v_pk_mul_f32 v[28:29], v[44:45], v[58:59] op_sel_hi:[1,0]
	s_add_i32 s0, s8, s17
	s_cmpk_gt_i32 s0, 0x3fff
	v_pk_mul_f32 v[18:19], v[104:105], v[18:19]
	v_pk_mul_f32 v[20:21], v[106:107], v[20:21]
	v_pk_mul_f32 v[14:15], v[104:105], v[26:27]
	v_pk_mul_f32 v[16:17], v[106:107], v[28:29]
	v_cvt_pk_bf16_f32 v18, v18, v19
	v_cvt_pk_bf16_f32 v19, v20, v21
	v_cvt_pk_bf16_f32 v14, v14, v15
	v_cvt_pk_bf16_f32 v15, v16, v17
	global_store_dwordx2 v[54:55], v[18:19], off offset:512 sc1
	global_store_dwordx2 v[56:57], v[14:15], off offset:512 sc1
	v_pk_mul_f32 v[18:19], v[34:35], v[22:23] op_sel_hi:[1,0]
	v_pk_mul_f32 v[20:21], v[36:37], v[22:23] op_sel_hi:[1,0]
	v_pk_mul_f32 v[26:27], v[50:51], v[58:59] op_sel_hi:[1,0]
	v_pk_mul_f32 v[28:29], v[52:53], v[58:59] op_sel_hi:[1,0]
	v_pk_mul_f32 v[18:19], v[18:19], v[108:109]
	v_pk_mul_f32 v[20:21], v[20:21], v[110:111]
	v_pk_mul_f32 v[14:15], v[108:109], v[26:27]
	v_pk_mul_f32 v[16:17], v[110:111], v[28:29]
	v_cvt_pk_bf16_f32 v18, v18, v19
	v_cvt_pk_bf16_f32 v19, v20, v21
	v_cvt_pk_bf16_f32 v14, v14, v15
	v_cvt_pk_bf16_f32 v15, v16, v17
	global_store_dwordx2 v[54:55], v[18:19], off offset:1024 sc1
	global_store_dwordx2 v[56:57], v[14:15], off offset:1024 sc1
	v_pk_mul_f32 v[18:19], v[30:31], v[22:23] op_sel_hi:[1,0]
	v_pk_mul_f32 v[20:21], v[32:33], v[22:23] op_sel_hi:[1,0]
	v_pk_mul_f32 v[22:23], v[46:47], v[58:59] op_sel_hi:[1,0]
	v_pk_mul_f32 v[26:27], v[48:49], v[58:59] op_sel_hi:[1,0]
	v_pk_mul_f32 v[18:19], v[18:19], v[112:113]
	v_pk_mul_f32 v[20:21], v[20:21], v[114:115]
	v_pk_mul_f32 v[14:15], v[22:23], v[112:113]
	v_pk_mul_f32 v[16:17], v[26:27], v[114:115]
	v_cvt_pk_bf16_f32 v18, v18, v19
	v_cvt_pk_bf16_f32 v19, v20, v21
	v_cvt_pk_bf16_f32 v14, v14, v15
	v_cvt_pk_bf16_f32 v15, v16, v17
	global_store_dwordx2 v[54:55], v[18:19], off offset:1536 sc1
	global_store_dwordx2 v[56:57], v[14:15], off offset:1536 sc1
	s_cbranch_scc0 .LBB0_57

; __device__ __forceinline__ void p0_prologue(const Ptrs& P, LAS unsigned char* lds, int vcu, int G) {
;     ...
;     for (int e = (vcu * 512 + tid); e < TT * 32; e += G * 512) {
;         const int row = e >> 5, j = e & 31;
;         const float inv = exp2f(-(float)j * (13.287712379549449f / 32.0f));
;         const float ang = (float)P.pos[row] * inv;
;         const double rev = (double)ang * 0.15915494309189535; const float fr = (float)(rev - __builtin_rint(rev));
;         cosT[e] = __builtin_amdgcn_cosf(fr); sinT[e] = __builtin_amdgcn_sinf(fr);
.LBB0_60:
	v_ashrrev_i32_e32 v6, 5, v0
	v_ashrrev_i32_e32 v7, 31, v6
	s_waitcnt lgkmcnt(0)
	v_lshl_add_u64 v[6:7], v[6:7], 2, s[58:59]
	global_load_dword v1, v[6:7], off sc1 nt
	v_add_co_u32_e32 v6, vcc, 0x200000, v2
	v_add_u32_e32 v0, s6, v0
	s_nop 0
	v_addc_co_u32_e32 v7, vcc, 0, v3, vcc
	v_cmp_lt_i32_e32 vcc, s7, v0
	s_or_b64 s[10:11], vcc, s[10:11]
	s_waitcnt vmcnt(0)
	v_cvt_f32_i32_e32 v1, v1
	v_mul_f32_e32 v1, v4, v1
	v_cvt_f64_f32_e32 v[8:9], v1
	v_mul_f64 v[10:11], v[8:9], s[12:13]
	v_rndne_f64_e32 v[10:11], v[10:11]
	v_fma_f64 v[8:9], v[8:9], s[12:13], -v[10:11]
	v_cvt_f32_f64_e32 v1, v[8:9]
	v_cos_f32_e32 v5, v1
	v_sin_f32_e32 v1, v1
	global_store_dword v[2:3], v5, off sc1
	global_store_dword v[6:7], v1, off sc1
	v_lshl_add_u64 v[2:3], v[2:3], 0, s[8:9]
	s_andn2_b64 exec, exec, s[10:11]
	s_cbranch_execnz .LBB0_60
